# gate chunks 0 and 1 of a row also loaded as one dwordx4 + swap (MLA latent epilogue, NA latent epilogues)
# baseline (speedup 1.0000x reference)
.LBB0_502:
	s_or_b64 exec, exec, s[16:17]
	v_permlane32_swap_b32_e32 v240, v242
	v_permlane32_swap_b32_e32 v241, v243
	v_permlane32_swap_b32_e32 v210, v212
	v_permlane32_swap_b32_e32 v211, v213
	v_permlane32_swap_b32_e32 v214, v216
	v_permlane32_swap_b32_e32 v215, v217
	v_permlane32_swap_b32_e32 v218, v220
	v_permlane32_swap_b32_e32 v219, v221
	v_permlane32_swap_b32_e32 v222, v224
	v_permlane32_swap_b32_e32 v223, v225
	v_permlane32_swap_b32_e32 v226, v228
	v_permlane32_swap_b32_e32 v227, v229
	v_permlane32_swap_b32_e32 v230, v232
	v_permlane32_swap_b32_e32 v231, v233
	v_permlane32_swap_b32_e32 v234, v236
	v_permlane32_swap_b32_e32 v235, v237
	v_add_f32_e32 v64, v64, v65
	v_fmac_f32_e32 v64, v186, v96
	v_rcp_f32_e32 v67, v64
	s_lshl_b64 s[14:15], s[14:15], 12
	s_add_u32 s14, s23, s14
	s_addc_u32 s15, s24, s15
	v_mul_f32_e32 v16, v67, v16
	v_mul_f32_e32 v17, v67, v17
	v_cvt_pk_bf16_f32 v80, v16, v17
	v_mul_f32_e32 v16, v67, v18
	v_mul_f32_e32 v17, v67, v19
	v_cvt_pk_bf16_f32 v81, v16, v17
	v_mul_f32_e32 v16, v67, v20
	v_mul_f32_e32 v17, v67, v21
	v_cvt_pk_bf16_f32 v82, v16, v17
	v_mul_f32_e32 v16, v67, v22
	v_mul_f32_e32 v17, v67, v23
	v_cvt_pk_bf16_f32 v83, v16, v17
	v_mul_f32_e32 v16, v67, v24
	v_mul_f32_e32 v17, v67, v25
	v_cvt_pk_bf16_f32 v84, v16, v17
	v_mul_f32_e32 v16, v67, v26
	v_mul_f32_e32 v17, v67, v27
	v_cvt_pk_bf16_f32 v85, v16, v17
	v_mul_f32_e32 v16, v67, v28
	v_mul_f32_e32 v17, v67, v29
	v_cvt_pk_bf16_f32 v86, v16, v17
	v_mul_f32_e32 v16, v67, v30
	v_mul_f32_e32 v17, v67, v31
	v_cvt_pk_bf16_f32 v87, v16, v17
	v_mul_f32_e32 v16, v67, v32
	v_mul_f32_e32 v17, v67, v33
	v_cvt_pk_bf16_f32 v88, v16, v17
	v_mul_f32_e32 v16, v67, v34
	v_mul_f32_e32 v17, v67, v35
	v_cvt_pk_bf16_f32 v89, v16, v17
	v_mul_f32_e32 v16, v67, v36
	v_mul_f32_e32 v17, v67, v37
	v_cvt_pk_bf16_f32 v90, v16, v17
	v_mul_f32_e32 v16, v67, v38
	v_mul_f32_e32 v17, v67, v39
	v_cvt_pk_bf16_f32 v91, v16, v17
	v_mul_f32_e32 v16, v67, v40
	v_mul_f32_e32 v17, v67, v41
	v_cvt_pk_bf16_f32 v92, v16, v17
	v_mul_f32_e32 v16, v67, v42
	v_mul_f32_e32 v17, v67, v43
	v_cvt_pk_bf16_f32 v93, v16, v17
	v_mul_f32_e32 v16, v67, v44
	v_mul_f32_e32 v17, v67, v45
	v_cvt_pk_bf16_f32 v94, v16, v17
	v_mul_f32_e32 v16, v67, v46
	v_mul_f32_e32 v17, v67, v47
	v_cvt_pk_bf16_f32 v95, v16, v17
	v_mul_f32_e32 v16, v67, v48
	v_mul_f32_e32 v17, v67, v49
	v_cvt_pk_bf16_f32 v76, v16, v17
	v_mul_f32_e32 v16, v67, v50
	v_mul_f32_e32 v17, v67, v51
	v_cvt_pk_bf16_f32 v77, v16, v17
	v_mul_f32_e32 v16, v67, v52
	v_mul_f32_e32 v17, v67, v53
	v_cvt_pk_bf16_f32 v78, v16, v17
	v_mul_f32_e32 v16, v67, v54
	v_mul_f32_e32 v17, v67, v55
	v_cvt_pk_bf16_f32 v79, v16, v17
	v_mul_f32_e32 v16, v67, v56
	v_mul_f32_e32 v17, v67, v57
	v_cvt_pk_bf16_f32 v72, v16, v17
	v_mul_f32_e32 v16, v67, v58
	v_mul_f32_e32 v17, v67, v59
	v_cvt_pk_bf16_f32 v73, v16, v17
	v_mul_f32_e32 v16, v67, v60
	v_mul_f32_e32 v17, v67, v61
	v_mul_f32_e32 v0, v67, v0
	v_mul_f32_e32 v1, v67, v1
	v_cvt_pk_bf16_f32 v74, v16, v17
	v_mul_f32_e32 v16, v67, v62
	v_mul_f32_e32 v17, v67, v63
	v_cvt_pk_bf16_f32 v75, v16, v17
	v_cvt_pk_bf16_f32 v68, v0, v1
	v_mul_f32_e32 v0, v67, v2
	v_mul_f32_e32 v1, v67, v3
	v_cvt_pk_bf16_f32 v69, v0, v1
	v_mul_f32_e32 v0, v67, v4
	v_mul_f32_e32 v1, v67, v5
	v_cvt_pk_bf16_f32 v70, v0, v1
	v_mul_f32_e32 v0, v67, v6
	v_mul_f32_e32 v1, v67, v7
	s_lshl_b32 s16, s0, 8
	v_cvt_pk_bf16_f32 v71, v0, v1
	v_mul_f32_e32 v0, v67, v8
	v_mul_f32_e32 v1, v67, v9
	s_add_u32 s14, s14, s16
	v_cvt_pk_bf16_f32 v64, v0, v1
	v_mul_f32_e32 v0, v67, v10
	v_mul_f32_e32 v1, v67, v11
	s_addc_u32 s15, s15, 0
	v_cvt_pk_bf16_f32 v65, v0, v1
	v_mul_f32_e32 v0, v67, v12
	v_mul_f32_e32 v1, v67, v13
	s_lshl_b32 s0, s0, 15
	v_cvt_pk_bf16_f32 v66, v0, v1
	v_mul_f32_e32 v0, v67, v14
	v_mul_f32_e32 v1, v67, v15
	v_lshl_add_u64 v[62:63], v[152:153], 0, s[0:1]
	v_lshlrev_b32_e32 v194, 3, v172
	v_mov_b32_e32 v195, 0
	v_lshl_add_u64 v[62:63], v[62:63], 0, v[194:195]
	v_cvt_pk_bf16_f32 v67, v0, v1
	global_load_dwordx4 v[0:3], v[62:63], off
	global_load_dwordx4 v[16:19], v[62:63], off offset:32
	global_load_dwordx4 v[20:23], v[62:63], off offset:64
	global_load_dwordx4 v[24:27], v[62:63], off offset:96
	global_load_dwordx4 v[28:31], v[62:63], off offset:128
	v_add_co_u32_e32 v48, vcc, s36, v62
	s_waitcnt vmcnt(0)
	v_permlane32_swap_b32_e32 v0, v2
	v_permlane32_swap_b32_e32 v1, v3
	v_permlane32_swap_b32_e32 v16, v18
	v_permlane32_swap_b32_e32 v17, v19
	v_permlane32_swap_b32_e32 v20, v22
	v_permlane32_swap_b32_e32 v21, v23
	v_permlane32_swap_b32_e32 v24, v26
	v_permlane32_swap_b32_e32 v25, v27
	v_permlane32_swap_b32_e32 v28, v30
	v_permlane32_swap_b32_e32 v29, v31
	s_nop 1
	v_mfma_f32_32x32x16_bf16 v[0:15], v[0:3], v[80:83], 0
	v_addc_co_u32_e32 v49, vcc, 0, v63, vcc
	v_add_co_u32_e32 v138, vcc, s37, v62
	s_add_i32 s41, s41, s60
	s_nop 0
	v_addc_co_u32_e32 v139, vcc, 0, v63, vcc
	v_mfma_f32_32x32x16_bf16 v[0:15], v[16:19], v[84:87], v[0:15]
	global_load_dwordx4 v[16:19], v[62:63], off offset:160
	v_add_co_u32_e32 v146, vcc, s40, v62
	s_cmpk_gt_i32 s41, 0x7ff
	s_nop 0
	v_addc_co_u32_e32 v147, vcc, 0, v63, vcc
	v_mfma_f32_32x32x16_bf16 v[0:15], v[20:23], v[88:91], v[0:15]
	global_load_dwordx4 v[20:23], v[62:63], off offset:192
	v_mfma_f32_32x32x16_bf16 v[0:15], v[24:27], v[92:95], v[0:15]
	global_load_dwordx4 v[24:27], v[48:49], off
	global_load_dwordx4 v[32:35], v[62:63], off offset:224
	global_load_dwordx4 v[36:39], v[48:49], off offset:32
	global_load_dwordx4 v[40:43], v[48:49], off offset:64
	global_load_dwordx4 v[44:47], v[48:49], off offset:96
	v_lshl_add_u64 v[62:63], s[14:15], 0, v[154:155]
	v_lshl_add_u64 v[96:97], v[62:63], 0, v[150:151]
	v_lshlrev_b32_e32 v198, 3, v172
	v_mov_b32_e32 v199, 0
	v_lshl_add_u64 v[198:199], v[96:97], 0, v[198:199]
	v_mfma_f32_32x32x16_bf16 v[0:15], v[28:31], v[76:79], v[0:15]
	s_waitcnt vmcnt(0)
	v_permlane32_swap_b32_e32 v16, v18
	v_permlane32_swap_b32_e32 v17, v19
	v_permlane32_swap_b32_e32 v20, v22
	v_permlane32_swap_b32_e32 v21, v23
	v_permlane32_swap_b32_e32 v24, v26
	v_permlane32_swap_b32_e32 v25, v27
	v_permlane32_swap_b32_e32 v32, v34
	v_permlane32_swap_b32_e32 v33, v35
	v_permlane32_swap_b32_e32 v36, v38
	v_permlane32_swap_b32_e32 v37, v39
	v_permlane32_swap_b32_e32 v40, v42
	v_permlane32_swap_b32_e32 v41, v43
	v_permlane32_swap_b32_e32 v44, v46
	v_permlane32_swap_b32_e32 v45, v47
	s_nop 1
	v_mfma_f32_32x32x16_bf16 v[0:15], v[16:19], v[72:75], v[0:15]
	v_mfma_f32_32x32x16_bf16 v[0:15], v[20:23], v[68:71], v[0:15]
	v_mfma_f32_32x32x16_bf16 v[0:15], v[32:35], v[64:67], v[0:15]
	global_load_dwordx4 v[32:35], v[138:139], off
	global_load_dwordx4 v[50:53], v[138:139], off offset:32
	global_load_dwordx4 v[54:57], v[138:139], off offset:64
	global_load_dwordx4 v[58:61], v[138:139], off offset:96
	global_load_dwordx4 v[98:101], v[146:147], off
	global_load_dwordx4 v[102:105], v[146:147], off offset:32
	global_load_dwordx4 v[106:109], v[146:147], off offset:64
	v_mfma_f32_32x32x16_bf16 v[16:31], v[24:27], v[80:83], 0
	global_load_dwordx4 v[110:113], v[146:147], off offset:96
	global_load_dwordx4 v[114:117], v[48:49], off offset:128
	global_load_dwordx4 v[118:121], v[48:49], off offset:160
	global_load_dwordx4 v[122:125], v[48:49], off offset:192
	global_load_dwordx4 v[126:129], v[48:49], off offset:224
	global_load_dwordx4 v[130:133], v[138:139], off offset:128
	global_load_dwordx4 v[134:137], v[138:139], off offset:160
	v_mfma_f32_32x32x16_bf16 v[16:31], v[36:39], v[84:87], v[16:31]
	v_mfma_f32_32x32x16_bf16 v[16:31], v[40:43], v[88:91], v[16:31]
	v_mfma_f32_32x32x16_bf16 v[16:31], v[44:47], v[92:95], v[16:31]
	s_waitcnt vmcnt(0)
	v_permlane32_swap_b32_e32 v32, v34
	v_permlane32_swap_b32_e32 v33, v35
	v_permlane32_swap_b32_e32 v50, v52
	v_permlane32_swap_b32_e32 v51, v53
	v_permlane32_swap_b32_e32 v54, v56
	v_permlane32_swap_b32_e32 v55, v57
	v_permlane32_swap_b32_e32 v58, v60
	v_permlane32_swap_b32_e32 v59, v61
	v_permlane32_swap_b32_e32 v98, v100
	v_permlane32_swap_b32_e32 v99, v101
	v_permlane32_swap_b32_e32 v102, v104
	v_permlane32_swap_b32_e32 v103, v105
	v_permlane32_swap_b32_e32 v106, v108
	v_permlane32_swap_b32_e32 v107, v109
	v_permlane32_swap_b32_e32 v110, v112
	v_permlane32_swap_b32_e32 v111, v113
	v_permlane32_swap_b32_e32 v114, v116
	v_permlane32_swap_b32_e32 v115, v117
	v_permlane32_swap_b32_e32 v118, v120
	v_permlane32_swap_b32_e32 v119, v121
	v_permlane32_swap_b32_e32 v122, v124
	v_permlane32_swap_b32_e32 v123, v125
	v_permlane32_swap_b32_e32 v126, v128
	v_permlane32_swap_b32_e32 v127, v129
	v_permlane32_swap_b32_e32 v130, v132
	v_permlane32_swap_b32_e32 v131, v133
	v_permlane32_swap_b32_e32 v134, v136
	v_permlane32_swap_b32_e32 v135, v137
	s_nop 1
	v_mfma_f32_32x32x16_bf16 v[32:47], v[32:35], v[80:83], 0
	v_mfma_f32_32x32x16_bf16 v[32:47], v[50:53], v[84:87], v[32:47]
	v_mfma_f32_32x32x16_bf16 v[32:47], v[54:57], v[88:91], v[32:47]
	v_mfma_f32_32x32x16_bf16 v[32:47], v[58:61], v[92:95], v[32:47]
	v_mfma_f32_32x32x16_bf16 v[48:63], v[98:101], v[80:83], 0
	global_load_dwordx4 v[80:83], v[138:139], off offset:192
	global_load_dwordx4 v[98:101], v[138:139], off offset:224
	s_nop 0
	global_load_dwordx4 v[138:141], v[146:147], off offset:128
	global_load_dwordx4 v[142:145], v[146:147], off offset:160
	v_mfma_f32_32x32x16_bf16 v[48:63], v[102:105], v[84:87], v[48:63]
	global_load_dwordx4 v[84:87], v[146:147], off offset:192
	global_load_dwordx4 v[102:105], v[146:147], off offset:224
	v_lshlrev_b32_e32 v146, 16, v240
	v_and_b32_e32 v147, 0xffff0000, v240
	v_lshlrev_b32_e32 v158, 16, v241
	v_mul_f32_e32 v0, v0, v146
	v_mul_f32_e32 v1, v1, v147
	v_cvt_pk_bf16_f32 v0, v0, v1
	v_mfma_f32_32x32x16_bf16 v[48:63], v[106:109], v[88:91], v[48:63]
	v_and_b32_e32 v88, 0xffff0000, v241
	v_mul_f32_e32 v1, v2, v158
	v_mul_f32_e32 v2, v3, v88
	v_cvt_pk_bf16_f32 v1, v1, v2
	s_nop 0
	v_mov_b32_e32 v200, v0
	v_mov_b32_e32 v201, v1
	v_mfma_f32_32x32x16_bf16 v[16:31], v[114:117], v[76:79], v[16:31]
	s_waitcnt vmcnt(0)
	v_permlane32_swap_b32_e32 v80, v82
	v_permlane32_swap_b32_e32 v81, v83
	v_permlane32_swap_b32_e32 v98, v100
	v_permlane32_swap_b32_e32 v99, v101
	v_permlane32_swap_b32_e32 v138, v140
	v_permlane32_swap_b32_e32 v139, v141
	v_permlane32_swap_b32_e32 v142, v144
	v_permlane32_swap_b32_e32 v143, v145
	v_permlane32_swap_b32_e32 v84, v86
	v_permlane32_swap_b32_e32 v85, v87
	v_permlane32_swap_b32_e32 v102, v104
	v_permlane32_swap_b32_e32 v103, v105
	s_nop 1
	v_lshlrev_b32_e32 v0, 16, v242
	v_and_b32_e32 v1, 0xffff0000, v242
	v_lshlrev_b32_e32 v2, 16, v243
	v_and_b32_e32 v3, 0xffff0000, v243
	v_mul_f32_e32 v0, v4, v0
	v_mul_f32_e32 v1, v5, v1
	v_mul_f32_e32 v2, v6, v2
	v_mul_f32_e32 v3, v7, v3
	v_cvt_pk_bf16_f32 v0, v0, v1
	v_cvt_pk_bf16_f32 v1, v2, v3
	v_mfma_f32_32x32x16_bf16 v[16:31], v[118:121], v[72:75], v[16:31]
	v_mov_b32_e32 v202, v0
	v_mov_b32_e32 v203, v1
	s_nop 1
	v_permlane32_swap_b32_e32 v200, v202
	v_permlane32_swap_b32_e32 v201, v203
	global_store_dwordx4 v[198:199], v[200:203], off
	v_lshlrev_b32_e32 v0, 16, v210
	v_and_b32_e32 v1, 0xffff0000, v210
	v_lshlrev_b32_e32 v2, 16, v211
	v_and_b32_e32 v3, 0xffff0000, v211
	v_mul_f32_e32 v0, v8, v0
	v_mul_f32_e32 v1, v9, v1
	v_mul_f32_e32 v2, v10, v2
	v_mul_f32_e32 v3, v11, v3
	v_cvt_pk_bf16_f32 v0, v0, v1
	v_cvt_pk_bf16_f32 v1, v2, v3
	v_mfma_f32_32x32x16_bf16 v[16:31], v[122:125], v[68:71], v[16:31]
	v_mov_b32_e32 v200, v0
	v_mov_b32_e32 v201, v1
	v_lshlrev_b32_e32 v0, 16, v212
	v_and_b32_e32 v1, 0xffff0000, v212
	v_lshlrev_b32_e32 v2, 16, v213
	v_and_b32_e32 v3, 0xffff0000, v213
	v_mul_f32_e32 v0, v12, v0
	v_mul_f32_e32 v1, v13, v1
	v_mul_f32_e32 v2, v14, v2
	v_mul_f32_e32 v3, v15, v3
	v_cvt_pk_bf16_f32 v0, v0, v1
	v_cvt_pk_bf16_f32 v1, v2, v3
	v_mfma_f32_32x32x16_bf16 v[16:31], v[126:129], v[64:67], v[16:31]
	v_mov_b32_e32 v202, v0
	v_mov_b32_e32 v203, v1
	s_nop 1
	v_permlane32_swap_b32_e32 v200, v202
	v_permlane32_swap_b32_e32 v201, v203
	global_store_dwordx4 v[198:199], v[200:203], off offset:32
	v_lshlrev_b32_e32 v0, 16, v214
	v_and_b32_e32 v1, 0xffff0000, v214
	v_lshlrev_b32_e32 v2, 16, v215
	v_and_b32_e32 v3, 0xffff0000, v215
	s_nop 5
	v_mul_f32_e32 v0, v16, v0
	v_mul_f32_e32 v1, v17, v1
	v_mul_f32_e32 v2, v18, v2
	v_mul_f32_e32 v3, v19, v3
	v_cvt_pk_bf16_f32 v0, v0, v1
	v_cvt_pk_bf16_f32 v1, v2, v3
	v_mfma_f32_32x32x16_bf16 v[32:47], v[130:133], v[76:79], v[32:47]
	v_mov_b32_e32 v200, v0
	v_mov_b32_e32 v201, v1
	v_lshlrev_b32_e32 v0, 16, v216
	v_and_b32_e32 v1, 0xffff0000, v216
	v_lshlrev_b32_e32 v2, 16, v217
	v_and_b32_e32 v3, 0xffff0000, v217
	v_mul_f32_e32 v0, v20, v0
	v_mul_f32_e32 v1, v21, v1
	v_mul_f32_e32 v2, v22, v2
	v_mul_f32_e32 v3, v23, v3
	v_cvt_pk_bf16_f32 v0, v0, v1
	v_cvt_pk_bf16_f32 v1, v2, v3
	v_mfma_f32_32x32x16_bf16 v[32:47], v[134:137], v[72:75], v[32:47]
	v_mov_b32_e32 v202, v0
	v_mov_b32_e32 v203, v1
	s_nop 1
	v_permlane32_swap_b32_e32 v200, v202
	v_permlane32_swap_b32_e32 v201, v203
	global_store_dwordx4 v[198:199], v[200:203], off offset:64
	v_lshlrev_b32_e32 v0, 16, v218
	v_and_b32_e32 v1, 0xffff0000, v218
	v_lshlrev_b32_e32 v2, 16, v219
	v_and_b32_e32 v3, 0xffff0000, v219
	v_mul_f32_e32 v0, v24, v0
	v_mul_f32_e32 v1, v25, v1
	v_mul_f32_e32 v2, v26, v2
	v_mul_f32_e32 v3, v27, v3
	v_cvt_pk_bf16_f32 v0, v0, v1
	v_cvt_pk_bf16_f32 v1, v2, v3
	v_mfma_f32_32x32x16_bf16 v[32:47], v[80:83], v[68:71], v[32:47]
	v_mov_b32_e32 v200, v0
	v_mov_b32_e32 v201, v1
	v_lshlrev_b32_e32 v0, 16, v220
	v_and_b32_e32 v1, 0xffff0000, v220
	v_lshlrev_b32_e32 v2, 16, v221
	v_and_b32_e32 v3, 0xffff0000, v221
	v_mul_f32_e32 v0, v28, v0
	v_mul_f32_e32 v1, v29, v1
	v_mul_f32_e32 v2, v30, v2
	v_mul_f32_e32 v3, v31, v3
	v_cvt_pk_bf16_f32 v0, v0, v1
	v_cvt_pk_bf16_f32 v1, v2, v3
	v_mfma_f32_32x32x16_bf16 v[32:47], v[98:101], v[64:67], v[32:47]
	v_mov_b32_e32 v202, v0
	v_mov_b32_e32 v203, v1
	s_nop 1
	v_permlane32_swap_b32_e32 v200, v202
	v_permlane32_swap_b32_e32 v201, v203
	global_store_dwordx4 v[198:199], v[200:203], off offset:96
	v_lshlrev_b32_e32 v0, 16, v222
	v_and_b32_e32 v1, 0xffff0000, v222
	v_lshlrev_b32_e32 v2, 16, v223
	v_and_b32_e32 v3, 0xffff0000, v223
	s_nop 5
	v_mul_f32_e32 v0, v32, v0
	v_mul_f32_e32 v1, v33, v1
	v_mul_f32_e32 v2, v34, v2
	v_mul_f32_e32 v3, v35, v3
	v_cvt_pk_bf16_f32 v0, v0, v1
	v_cvt_pk_bf16_f32 v1, v2, v3
	v_mfma_f32_32x32x16_bf16 v[48:63], v[110:113], v[92:95], v[48:63]
	v_mov_b32_e32 v200, v0
	v_mov_b32_e32 v201, v1
	v_lshlrev_b32_e32 v0, 16, v224
	v_and_b32_e32 v1, 0xffff0000, v224
	v_lshlrev_b32_e32 v2, 16, v225
	v_and_b32_e32 v3, 0xffff0000, v225
	v_mul_f32_e32 v0, v36, v0
	v_mul_f32_e32 v1, v37, v1
	v_mul_f32_e32 v2, v38, v2
	v_mul_f32_e32 v3, v39, v3
	v_cvt_pk_bf16_f32 v0, v0, v1
	v_cvt_pk_bf16_f32 v1, v2, v3
	v_mfma_f32_32x32x16_bf16 v[48:63], v[138:141], v[76:79], v[48:63]
	v_mov_b32_e32 v202, v0
	v_mov_b32_e32 v203, v1
	s_nop 1
	v_permlane32_swap_b32_e32 v200, v202
	v_permlane32_swap_b32_e32 v201, v203
	global_store_dwordx4 v[198:199], v[200:203], off offset:128
	v_lshlrev_b32_e32 v0, 16, v226
	v_and_b32_e32 v1, 0xffff0000, v226
	v_lshlrev_b32_e32 v2, 16, v227
	v_and_b32_e32 v3, 0xffff0000, v227
	v_mul_f32_e32 v0, v40, v0
	v_mul_f32_e32 v1, v41, v1
	v_mul_f32_e32 v2, v42, v2
	v_mul_f32_e32 v3, v43, v3
	v_cvt_pk_bf16_f32 v0, v0, v1
	v_cvt_pk_bf16_f32 v1, v2, v3
	v_mfma_f32_32x32x16_bf16 v[48:63], v[142:145], v[72:75], v[48:63]
	v_mov_b32_e32 v200, v0
	v_mov_b32_e32 v201, v1
	v_lshlrev_b32_e32 v0, 16, v228
	v_and_b32_e32 v1, 0xffff0000, v228
	v_lshlrev_b32_e32 v2, 16, v229
	v_and_b32_e32 v3, 0xffff0000, v229
	v_mul_f32_e32 v0, v44, v0
	v_mul_f32_e32 v1, v45, v1
	v_mul_f32_e32 v2, v46, v2
	v_mul_f32_e32 v3, v47, v3
	v_cvt_pk_bf16_f32 v0, v0, v1
	v_cvt_pk_bf16_f32 v1, v2, v3
	v_mfma_f32_32x32x16_bf16 v[48:63], v[84:87], v[68:71], v[48:63]
	v_mov_b32_e32 v202, v0
	v_mov_b32_e32 v203, v1
	s_nop 1
	v_permlane32_swap_b32_e32 v200, v202
	v_permlane32_swap_b32_e32 v201, v203
	global_store_dwordx4 v[198:199], v[200:203], off offset:160
	v_lshlrev_b32_e32 v0, 16, v230
	v_mfma_f32_32x32x16_bf16 v[48:63], v[102:105], v[64:67], v[48:63]
	v_and_b32_e32 v1, 0xffff0000, v230
	v_lshlrev_b32_e32 v2, 16, v231
	v_and_b32_e32 v3, 0xffff0000, v231
	s_nop 8
	v_mul_f32_e32 v0, v48, v0
	v_mul_f32_e32 v1, v49, v1
	v_mul_f32_e32 v2, v50, v2
	v_mul_f32_e32 v3, v51, v3
	v_cvt_pk_bf16_f32 v0, v0, v1
	v_cvt_pk_bf16_f32 v1, v2, v3
	s_nop 0
	v_mov_b32_e32 v200, v0
	v_mov_b32_e32 v201, v1
	v_lshlrev_b32_e32 v0, 16, v232
	v_and_b32_e32 v1, 0xffff0000, v232
	v_lshlrev_b32_e32 v2, 16, v233
	v_and_b32_e32 v3, 0xffff0000, v233
	v_mul_f32_e32 v0, v52, v0
	v_mul_f32_e32 v1, v53, v1
	v_mul_f32_e32 v2, v54, v2
	v_mul_f32_e32 v3, v55, v3
	v_cvt_pk_bf16_f32 v0, v0, v1
	v_cvt_pk_bf16_f32 v1, v2, v3
	s_nop 0
	v_mov_b32_e32 v202, v0
	v_mov_b32_e32 v203, v1
	s_nop 1
	v_permlane32_swap_b32_e32 v200, v202
	v_permlane32_swap_b32_e32 v201, v203
	global_store_dwordx4 v[198:199], v[200:203], off offset:192
	v_lshlrev_b32_e32 v0, 16, v234
	v_and_b32_e32 v1, 0xffff0000, v234
	v_lshlrev_b32_e32 v2, 16, v235
	v_and_b32_e32 v3, 0xffff0000, v235
	v_mul_f32_e32 v0, v56, v0
	v_mul_f32_e32 v1, v57, v1
	v_mul_f32_e32 v2, v58, v2
	v_mul_f32_e32 v3, v59, v3
	v_cvt_pk_bf16_f32 v0, v0, v1
	v_cvt_pk_bf16_f32 v1, v2, v3
	s_nop 0
	v_mov_b32_e32 v200, v0
	v_mov_b32_e32 v201, v1
	v_lshlrev_b32_e32 v0, 16, v236
	v_and_b32_e32 v1, 0xffff0000, v236
	v_lshlrev_b32_e32 v2, 16, v237
	v_and_b32_e32 v3, 0xffff0000, v237
	v_mul_f32_e32 v0, v60, v0
	v_mul_f32_e32 v1, v61, v1
	v_mul_f32_e32 v2, v62, v2
	v_mul_f32_e32 v3, v63, v3
	v_cvt_pk_bf16_f32 v0, v0, v1
	v_cvt_pk_bf16_f32 v1, v2, v3
	v_mov_b32_e32 v202, v0
	v_mov_b32_e32 v203, v1
	s_nop 1
	v_permlane32_swap_b32_e32 v200, v202
	v_permlane32_swap_b32_e32 v201, v203
	global_store_dwordx4 v[198:199], v[200:203], off offset:224
	s_waitcnt lgkmcnt(0)
	s_barrier
	s_cbranch_scc1 .LBB0_525

.LBB0_519:
	s_lshl_b64 s[98:99], s[14:15], 12
	s_add_u32 s98, s23, s98
	s_addc_u32 s99, s24, s99
	s_lshl_b32 s100, s0, 8
	s_add_u32 s98, s98, s100
	s_addc_u32 s99, s99, 0
	v_lshl_add_u64 v[208:209], s[98:99], 0, v[154:155]
	v_lshl_add_u64 v[208:209], v[208:209], 0, v[150:151]
	v_lshlrev_b32_e32 v196, 3, v172
	v_mov_b32_e32 v197, 0
	v_lshl_add_u64 v[196:197], v[208:209], 0, v[196:197]
	global_load_dwordx4 v[210:213], v[196:197], off offset:32
	global_load_dwordx4 v[214:217], v[196:197], off offset:64
	global_load_dwordx4 v[218:221], v[196:197], off offset:96
	global_load_dwordx4 v[222:225], v[196:197], off offset:128
	global_load_dwordx4 v[226:229], v[196:197], off offset:160
	global_load_dwordx4 v[230:233], v[196:197], off offset:192
	global_load_dwordx4 v[234:237], v[196:197], off offset:224
	global_load_dwordx4 v[240:243], v[196:197], off
	s_nop 4
	v_max_f32_e32 v96, v81, v81
	v_max_f32_e32 v97, v80, v80
	v_max_f32_e32 v96, v97, v96
	v_max3_f32 v96, v96, v82, v83
	v_max3_f32 v96, v96, v84, v85
	v_max3_f32 v96, v96, v86, v87
	v_max3_f32 v96, v96, v88, v89
	v_max3_f32 v96, v96, v90, v91
	v_max3_f32 v96, v96, v92, v93
	v_max3_f32 v96, v96, v94, v95
	v_max3_f32 v96, v96, v64, v65
	v_max3_f32 v96, v96, v66, v67
	v_max3_f32 v96, v96, v68, v69
	v_max3_f32 v96, v96, v70, v71
	v_max3_f32 v96, v96, v72, v73
	v_max3_f32 v96, v96, v74, v75
	v_max3_f32 v96, v96, v76, v77
	v_max3_f32 v96, v96, v78, v79
	v_mov_b32_e32 v97, v96
	s_nop 1
	v_permlane32_swap_b32_e32 v96, v97
	v_max_f32_e32 v97, v97, v97
	v_max_f32_e32 v96, v96, v96
	v_max_f32_e32 v97, v96, v97
	v_cmp_ge_f32_e32 vcc, s39, v97
	s_cmp_eq_u64 vcc, exec
	v_mov_b32_e32 v96, 1.0
	s_cbranch_scc0 .LBB0_524
	v_cmp_gt_f32_e32 vcc, 1.0, v96
	s_cbranch_vccz .LBB0_522

.LBB0_1084:
	v_mov_b32_e32 v151, v149
	v_lshl_add_u64 v[32:33], s[94:95], 0, v[150:151]
	v_lshlrev_b32_e32 v34, 1, v144
	v_mov_b32_e32 v35, v149
	v_lshl_add_u64 v[32:33], v[32:33], 0, v[34:35]
	v_bfe_u32 v198, v192, 5, 1
	v_lshlrev_b32_e32 v198, 3, v198
	v_mov_b32_e32 v199, 0
	v_lshl_add_u64 v[198:199], v[32:33], 0, v[198:199]
	v_rcp_f32_e32 v36, v127
	s_waitcnt vmcnt(0)
	v_permlane32_swap_b32_e32 v210, v212
	v_permlane32_swap_b32_e32 v211, v213
	v_permlane32_swap_b32_e32 v242, v244
	v_permlane32_swap_b32_e32 v243, v245
	v_permlane32_swap_b32_e32 v246, v248
	v_permlane32_swap_b32_e32 v247, v249
	v_permlane32_swap_b32_e32 v250, v252
	v_permlane32_swap_b32_e32 v251, v253
	s_nop 0
	v_lshlrev_b32_e32 v37, 16, v210
	v_mul_f32_e32 v16, v16, v36
	v_mul_f32_e32 v17, v17, v36
	v_mul_f32_e32 v18, v18, v36
	v_mul_f32_e32 v19, v19, v36
	v_and_b32_e32 v34, 0xffff0000, v210
	v_lshlrev_b32_e32 v38, 16, v211
	v_and_b32_e32 v35, 0xffff0000, v211
	v_mul_f32_e32 v16, v16, v37
	v_mul_f32_e32 v17, v17, v34
	v_mul_f32_e32 v18, v18, v38
	v_mul_f32_e32 v19, v19, v35
	v_cvt_pk_bf16_f32 v16, v16, v17
	v_cvt_pk_bf16_f32 v17, v18, v19
	v_mul_f32_e32 v20, v20, v36
	v_mul_f32_e32 v21, v21, v36
	v_mul_f32_e32 v22, v22, v36
	v_mul_f32_e32 v23, v23, v36
	v_mov_b32_e32 v200, v16
	v_mov_b32_e32 v201, v17
	v_mul_f32_e32 v0, v0, v36
	v_mul_f32_e32 v1, v1, v36
	v_mul_f32_e32 v2, v2, v36
	v_mul_f32_e32 v3, v3, v36
	v_mul_f32_e32 v4, v4, v36
	v_mul_f32_e32 v5, v5, v36
	v_mul_f32_e32 v6, v6, v36
	v_mul_f32_e32 v7, v7, v36
	v_lshlrev_b32_e32 v16, 16, v212
	v_and_b32_e32 v17, 0xffff0000, v212
	v_lshlrev_b32_e32 v18, 16, v213
	v_and_b32_e32 v19, 0xffff0000, v213
	v_mul_f32_e32 v16, v20, v16
	v_mul_f32_e32 v17, v21, v17
	v_mul_f32_e32 v18, v22, v18
	v_mul_f32_e32 v19, v23, v19
	v_cvt_pk_bf16_f32 v16, v16, v17
	v_cvt_pk_bf16_f32 v17, v18, v19
	v_mul_f32_e32 v20, v24, v36
	v_mul_f32_e32 v21, v25, v36
	v_mul_f32_e32 v22, v26, v36
	v_mul_f32_e32 v23, v27, v36
	v_mov_b32_e32 v202, v16
	v_mov_b32_e32 v203, v17
	s_nop 1
	v_permlane32_swap_b32_e32 v200, v202
	v_permlane32_swap_b32_e32 v201, v203
	global_store_dwordx4 v[198:199], v[200:203], off
	v_lshlrev_b32_e32 v16, 16, v242
	v_and_b32_e32 v17, 0xffff0000, v242
	v_lshlrev_b32_e32 v18, 16, v243
	v_and_b32_e32 v19, 0xffff0000, v243
	v_mul_f32_e32 v16, v20, v16
	v_mul_f32_e32 v17, v21, v17
	v_mul_f32_e32 v18, v22, v18
	v_mul_f32_e32 v19, v23, v19
	v_cvt_pk_bf16_f32 v16, v16, v17
	v_cvt_pk_bf16_f32 v17, v18, v19
	v_mul_f32_e32 v20, v28, v36
	v_mul_f32_e32 v21, v29, v36
	v_mul_f32_e32 v22, v30, v36
	v_mul_f32_e32 v23, v31, v36
	v_mov_b32_e32 v200, v16
	v_mov_b32_e32 v201, v17
	v_lshlrev_b32_e32 v16, 16, v244
	v_and_b32_e32 v17, 0xffff0000, v244
	v_lshlrev_b32_e32 v18, 16, v245
	v_and_b32_e32 v19, 0xffff0000, v245
	v_mul_f32_e32 v16, v20, v16
	v_mul_f32_e32 v17, v21, v17
	v_mul_f32_e32 v18, v22, v18
	v_mul_f32_e32 v19, v23, v19
	v_cvt_pk_bf16_f32 v16, v16, v17
	v_cvt_pk_bf16_f32 v17, v18, v19
	s_nop 0
	v_mov_b32_e32 v202, v16
	v_mov_b32_e32 v203, v17
	s_nop 1
	v_permlane32_swap_b32_e32 v200, v202
	v_permlane32_swap_b32_e32 v201, v203
	global_store_dwordx4 v[198:199], v[200:203], off offset:32
	v_lshlrev_b32_e32 v16, 16, v246
	v_and_b32_e32 v17, 0xffff0000, v246
	v_lshlrev_b32_e32 v18, 16, v247
	v_and_b32_e32 v19, 0xffff0000, v247
	v_mul_f32_e32 v0, v0, v16
	v_mul_f32_e32 v1, v1, v17
	v_mul_f32_e32 v2, v2, v18
	v_mul_f32_e32 v3, v3, v19
	v_cvt_pk_bf16_f32 v0, v0, v1
	v_cvt_pk_bf16_f32 v1, v2, v3
	s_nop 0
	v_mov_b32_e32 v200, v0
	v_mov_b32_e32 v201, v1
	v_lshlrev_b32_e32 v0, 16, v248
	v_and_b32_e32 v1, 0xffff0000, v248
	v_lshlrev_b32_e32 v2, 16, v249
	v_and_b32_e32 v3, 0xffff0000, v249
	v_mul_f32_e32 v0, v4, v0
	v_mul_f32_e32 v1, v5, v1
	v_mul_f32_e32 v2, v6, v2
	v_mul_f32_e32 v3, v7, v3
	v_cvt_pk_bf16_f32 v0, v0, v1
	v_cvt_pk_bf16_f32 v1, v2, v3
	v_mul_f32_e32 v4, v8, v36
	v_mul_f32_e32 v5, v9, v36
	v_mul_f32_e32 v6, v10, v36
	v_mul_f32_e32 v7, v11, v36
	v_mov_b32_e32 v202, v0
	v_mov_b32_e32 v203, v1
	s_nop 1
	v_permlane32_swap_b32_e32 v200, v202
	v_permlane32_swap_b32_e32 v201, v203
	global_store_dwordx4 v[198:199], v[200:203], off offset:64
	v_lshlrev_b32_e32 v0, 16, v250
	v_and_b32_e32 v1, 0xffff0000, v250
	v_lshlrev_b32_e32 v2, 16, v251
	v_and_b32_e32 v3, 0xffff0000, v251
	v_mul_f32_e32 v0, v4, v0
	v_mul_f32_e32 v1, v5, v1
	v_mul_f32_e32 v2, v6, v2
	v_mul_f32_e32 v3, v7, v3
	v_cvt_pk_bf16_f32 v0, v0, v1
	v_cvt_pk_bf16_f32 v1, v2, v3
	v_mul_f32_e32 v4, v12, v36
	v_mul_f32_e32 v5, v13, v36
	v_mov_b32_e32 v200, v0
	v_mov_b32_e32 v201, v1
	v_mul_f32_e32 v6, v14, v36
	v_mul_f32_e32 v7, v15, v36
	v_lshlrev_b32_e32 v0, 16, v252
	v_and_b32_e32 v1, 0xffff0000, v252
	v_lshlrev_b32_e32 v2, 16, v253
	v_and_b32_e32 v3, 0xffff0000, v253
	v_mul_f32_e32 v0, v4, v0
	v_mul_f32_e32 v1, v5, v1
	v_mul_f32_e32 v2, v6, v2
	v_mul_f32_e32 v3, v7, v3
	v_cvt_pk_bf16_f32 v0, v0, v1
	v_cvt_pk_bf16_f32 v1, v2, v3
	v_mov_b32_e32 v202, v0
	v_mov_b32_e32 v203, v1
	s_nop 1
	v_permlane32_swap_b32_e32 v200, v202
	v_permlane32_swap_b32_e32 v201, v203
	global_store_dwordx4 v[198:199], v[200:203], off offset:96
	s_barrier

.LBB0_1317:
	v_mov_b32_e32 v204, v150
	v_mov_b32_e32 v205, v149
	v_lshl_add_u64 v[206:207], s[94:95], 0, v[204:205]
	v_lshlrev_b32_e32 v204, 1, v144
	v_lshl_add_u64 v[206:207], v[206:207], 0, v[204:205]
	v_bfe_u32 v208, v192, 5, 1
	v_lshlrev_b32_e32 v208, 3, v208
	v_mov_b32_e32 v209, 0
	v_lshl_add_u64 v[208:209], v[206:207], 0, v[208:209]
	global_load_dwordx4 v[210:213], v[208:209], off
	global_load_dwordx4 v[242:245], v[208:209], off offset:32
	global_load_dwordx4 v[246:249], v[208:209], off offset:64
	global_load_dwordx4 v[250:253], v[208:209], off offset:96
	s_and_b64 vcc, exec, s[70:71]
	s_cbranch_vccnz .LBB0_1319
	v_exp_f32_e32 v36, v48
	v_add_f32_e32 v33, 0, v166
	v_exp_f32_e32 v37, v49
	v_add_f32_e32 v33, v167, v33
	v_exp_f32_e32 v38, v50
	v_add_f32_e32 v33, v168, v33
	v_exp_f32_e32 v39, v51
	v_add_f32_e32 v33, v169, v33
	v_exp_f32_e32 v40, v52
	v_add_f32_e32 v33, v36, v33
	v_exp_f32_e32 v41, v53
	v_add_f32_e32 v33, v37, v33
	v_exp_f32_e32 v42, v54
	v_add_f32_e32 v33, v38, v33
	v_exp_f32_e32 v43, v55
	v_add_f32_e32 v33, v39, v33
	v_exp_f32_e32 v44, v56
	v_add_f32_e32 v33, v40, v33
	v_exp_f32_e32 v45, v57
	v_add_f32_e32 v33, v41, v33
	v_exp_f32_e32 v46, v58
	v_add_f32_e32 v33, v42, v33
	v_exp_f32_e32 v47, v59
	v_add_f32_e32 v33, v43, v33
	v_exp_f32_e32 v48, v60
	v_add_f32_e32 v33, v44, v33
	v_exp_f32_e32 v49, v61
	v_add_f32_e32 v33, v45, v33
	v_exp_f32_e32 v50, v62
	v_add_f32_e32 v33, v46, v33
	v_exp_f32_e32 v51, v63
	v_add_f32_e32 v33, v47, v33
	v_add_f32_e32 v33, v48, v33
	v_add_f32_e32 v33, v49, v33
	v_add_f32_e32 v33, v50, v33
	v_add_f32_e32 v33, v51, v33
	v_mov_b32_e32 v34, v33
	s_nop 1
	v_permlane32_swap_b32_e32 v33, v34
	v_add_f32_e32 v64, v33, v34
	v_fmac_f32_e32 v64, v176, v32
	v_cvt_pk_bf16_f32 v32, v149, v149
	v_cvt_pk_bf16_f32 v33, v149, v149
	v_cvt_pk_bf16_f32 v34, v166, v167
	v_cvt_pk_bf16_f32 v35, v168, v169
	v_cvt_pk_bf16_f32 v36, v36, v37
	v_cvt_pk_bf16_f32 v37, v38, v39
	v_cvt_pk_bf16_f32 v38, v40, v41
	v_cvt_pk_bf16_f32 v39, v42, v43
	v_cvt_pk_bf16_f32 v40, v44, v45
	v_cvt_pk_bf16_f32 v41, v46, v47
	v_cvt_pk_bf16_f32 v42, v48, v49
	v_cvt_pk_bf16_f32 v43, v50, v51
	ds_read_b64_tr_b16 v[44:45], v185 offset:0
	ds_read_b64_tr_b16 v[46:47], v185 offset:0x400
	ds_read_b64_tr_b16 v[48:49], v185 offset:0x800
	ds_read_b64_tr_b16 v[50:51], v185 offset:0xc00
	ds_read_b64_tr_b16 v[52:53], v185 offset:0x1000
	ds_read_b64_tr_b16 v[54:55], v185 offset:0x1400
	ds_read_b64_tr_b16 v[56:57], v185 offset:0x1800
	ds_read_b64_tr_b16 v[58:59], v185 offset:0x1c00
	s_waitcnt lgkmcnt(0)
	s_mov_b32 s77, s76
	s_mov_b32 s78, s76
	s_mov_b32 s79, s76
	v_mov_b64_e32 v[60:61], s[76:77]
	v_mov_b64_e32 v[62:63], s[78:79]
	s_nop 1
	v_mfma_f32_32x32x16_bf16 v[16:31], v[44:47], v[60:63], v[16:31]
	ds_read_b64_tr_b16 v[44:45], v185 offset:0x200
	ds_read_b64_tr_b16 v[46:47], v185 offset:0x600
	v_mfma_f32_32x32x16_bf16 v[16:31], v[48:51], v[32:35], v[16:31]
	ds_read_b64_tr_b16 v[48:49], v185 offset:0xa00
	ds_read_b64_tr_b16 v[50:51], v185 offset:0xe00
	v_mfma_f32_32x32x16_bf16 v[16:31], v[52:55], v[36:39], v[16:31]
	ds_read_b64_tr_b16 v[52:53], v185 offset:0x1200
	ds_read_b64_tr_b16 v[54:55], v185 offset:0x1600
	v_mfma_f32_32x32x16_bf16 v[16:31], v[56:59], v[40:43], v[16:31]
	ds_read_b64_tr_b16 v[56:57], v185 offset:0x1a00
	ds_read_b64_tr_b16 v[58:59], v185 offset:0x1e00
	s_waitcnt lgkmcnt(0)
	v_mfma_f32_32x32x16_bf16 v[0:15], v[44:47], v[60:63], v[0:15]
	v_mov_b32_e32 v176, v64
	v_mfma_f32_32x32x16_bf16 v[0:15], v[48:51], v[32:35], v[0:15]
	v_mfma_f32_32x32x16_bf16 v[0:15], v[52:55], v[36:39], v[0:15]
	v_mfma_f32_32x32x16_bf16 v[0:15], v[56:59], v[40:43], v[0:15]
.LBB0_1319:
	v_mov_b32_e32 v151, v149
	v_lshl_add_u64 v[32:33], s[94:95], 0, v[150:151]
	v_lshlrev_b32_e32 v34, 1, v144
	v_mov_b32_e32 v35, v149
	v_lshl_add_u64 v[32:33], v[32:33], 0, v[34:35]
	v_bfe_u32 v198, v192, 5, 1
	v_lshlrev_b32_e32 v198, 3, v198
	v_mov_b32_e32 v199, 0
	v_lshl_add_u64 v[198:199], v[32:33], 0, v[198:199]
	v_rcp_f32_e32 v36, v176
	s_mov_b64 s[70:71], 0
	v_mul_f32_e32 v16, v16, v36
	v_mul_f32_e32 v17, v17, v36
	v_mul_f32_e32 v18, v18, v36
	v_mul_f32_e32 v19, v19, v36
	v_mul_f32_e32 v20, v20, v36
	v_mul_f32_e32 v21, v21, v36
	v_mul_f32_e32 v22, v22, v36
	v_mul_f32_e32 v23, v23, v36
	v_mul_f32_e32 v0, v0, v36
	v_mul_f32_e32 v1, v1, v36
	v_mul_f32_e32 v2, v2, v36
	v_mul_f32_e32 v3, v3, v36
	v_mul_f32_e32 v4, v4, v36
	v_mul_f32_e32 v5, v5, v36
	v_mul_f32_e32 v6, v6, v36
	v_mul_f32_e32 v7, v7, v36
	s_waitcnt vmcnt(0)
	v_permlane32_swap_b32_e32 v210, v212
	v_permlane32_swap_b32_e32 v211, v213
	v_permlane32_swap_b32_e32 v242, v244
	v_permlane32_swap_b32_e32 v243, v245
	v_permlane32_swap_b32_e32 v246, v248
	v_permlane32_swap_b32_e32 v247, v249
	v_permlane32_swap_b32_e32 v250, v252
	v_permlane32_swap_b32_e32 v251, v253
	s_nop 0
	v_lshlrev_b32_e32 v37, 16, v210
	v_and_b32_e32 v34, 0xffff0000, v210
	v_lshlrev_b32_e32 v38, 16, v211
	v_and_b32_e32 v35, 0xffff0000, v211
	v_mul_f32_e32 v16, v16, v37
	v_mul_f32_e32 v17, v17, v34
	v_mul_f32_e32 v18, v18, v38
	v_mul_f32_e32 v19, v19, v35
	v_cvt_pk_bf16_f32 v16, v16, v17
	v_cvt_pk_bf16_f32 v17, v18, v19
	s_nop 0
	v_mov_b32_e32 v200, v16
	v_mov_b32_e32 v201, v17
	v_lshlrev_b32_e32 v16, 16, v212
	v_and_b32_e32 v17, 0xffff0000, v212
	v_lshlrev_b32_e32 v18, 16, v213
	v_and_b32_e32 v19, 0xffff0000, v213
	v_mul_f32_e32 v16, v20, v16
	v_mul_f32_e32 v17, v21, v17
	v_mul_f32_e32 v18, v22, v18
	v_mul_f32_e32 v19, v23, v19
	v_cvt_pk_bf16_f32 v16, v16, v17
	v_cvt_pk_bf16_f32 v17, v18, v19
	v_mul_f32_e32 v20, v24, v36
	v_mul_f32_e32 v21, v25, v36
	v_mul_f32_e32 v22, v26, v36
	v_mul_f32_e32 v23, v27, v36
	v_mov_b32_e32 v202, v16
	v_mov_b32_e32 v203, v17
	s_nop 1
	v_permlane32_swap_b32_e32 v200, v202
	v_permlane32_swap_b32_e32 v201, v203
	global_store_dwordx4 v[198:199], v[200:203], off
	v_lshlrev_b32_e32 v16, 16, v242
	v_and_b32_e32 v17, 0xffff0000, v242
	v_lshlrev_b32_e32 v18, 16, v243
	v_and_b32_e32 v19, 0xffff0000, v243
	v_mul_f32_e32 v16, v20, v16
	v_mul_f32_e32 v17, v21, v17
	v_mul_f32_e32 v18, v22, v18
	v_mul_f32_e32 v19, v23, v19
	v_cvt_pk_bf16_f32 v16, v16, v17
	v_cvt_pk_bf16_f32 v17, v18, v19
	v_mul_f32_e32 v20, v28, v36
	v_mul_f32_e32 v21, v29, v36
	v_mul_f32_e32 v22, v30, v36
	v_mul_f32_e32 v23, v31, v36
	v_mov_b32_e32 v200, v16
	v_mov_b32_e32 v201, v17
	v_lshlrev_b32_e32 v16, 16, v244
	v_and_b32_e32 v17, 0xffff0000, v244
	v_lshlrev_b32_e32 v18, 16, v245
	v_and_b32_e32 v19, 0xffff0000, v245
	v_mul_f32_e32 v16, v20, v16
	v_mul_f32_e32 v17, v21, v17
	v_mul_f32_e32 v18, v22, v18
	v_mul_f32_e32 v19, v23, v19
	v_cvt_pk_bf16_f32 v16, v16, v17
	v_cvt_pk_bf16_f32 v17, v18, v19
	s_nop 0
	v_mov_b32_e32 v202, v16
	v_mov_b32_e32 v203, v17
	s_nop 1
	v_permlane32_swap_b32_e32 v200, v202
	v_permlane32_swap_b32_e32 v201, v203
	global_store_dwordx4 v[198:199], v[200:203], off offset:32
	v_lshlrev_b32_e32 v16, 16, v246
	v_and_b32_e32 v17, 0xffff0000, v246
	v_lshlrev_b32_e32 v18, 16, v247
	v_and_b32_e32 v19, 0xffff0000, v247
	v_mul_f32_e32 v0, v0, v16
	v_mul_f32_e32 v1, v1, v17
	v_mul_f32_e32 v2, v2, v18
	v_mul_f32_e32 v3, v3, v19
	v_cvt_pk_bf16_f32 v0, v0, v1
	v_cvt_pk_bf16_f32 v1, v2, v3
	s_nop 0
	v_mov_b32_e32 v200, v0
	v_mov_b32_e32 v201, v1
	v_lshlrev_b32_e32 v0, 16, v248
	v_and_b32_e32 v1, 0xffff0000, v248
	v_lshlrev_b32_e32 v2, 16, v249
	v_and_b32_e32 v3, 0xffff0000, v249
	v_mul_f32_e32 v0, v4, v0
	v_mul_f32_e32 v1, v5, v1
	v_mul_f32_e32 v2, v6, v2
	v_mul_f32_e32 v3, v7, v3
	v_cvt_pk_bf16_f32 v0, v0, v1
	v_cvt_pk_bf16_f32 v1, v2, v3
	v_mul_f32_e32 v4, v8, v36
	v_mul_f32_e32 v5, v9, v36
	v_mul_f32_e32 v6, v10, v36
	v_mul_f32_e32 v7, v11, v36
	v_mov_b32_e32 v202, v0
	v_mov_b32_e32 v203, v1
	s_nop 1
	v_permlane32_swap_b32_e32 v200, v202
	v_permlane32_swap_b32_e32 v201, v203
	global_store_dwordx4 v[198:199], v[200:203], off offset:64
	v_lshlrev_b32_e32 v0, 16, v250
	v_and_b32_e32 v1, 0xffff0000, v250
	v_lshlrev_b32_e32 v2, 16, v251
	v_and_b32_e32 v3, 0xffff0000, v251
	v_mul_f32_e32 v0, v4, v0
	v_mul_f32_e32 v1, v5, v1
	v_mul_f32_e32 v2, v6, v2
	v_mul_f32_e32 v3, v7, v3
	v_cvt_pk_bf16_f32 v0, v0, v1
	v_cvt_pk_bf16_f32 v1, v2, v3
	v_mul_f32_e32 v4, v12, v36
	v_mul_f32_e32 v5, v13, v36
	v_mov_b32_e32 v200, v0
	v_mov_b32_e32 v201, v1
	v_mul_f32_e32 v6, v14, v36
	v_mul_f32_e32 v7, v15, v36
	v_lshlrev_b32_e32 v0, 16, v252
	v_and_b32_e32 v1, 0xffff0000, v252
	v_lshlrev_b32_e32 v2, 16, v253
	v_and_b32_e32 v3, 0xffff0000, v253
	v_mul_f32_e32 v0, v4, v0
	v_mul_f32_e32 v1, v5, v1
	v_mul_f32_e32 v2, v6, v2
	v_mul_f32_e32 v3, v7, v3
	v_cvt_pk_bf16_f32 v0, v0, v1
	v_cvt_pk_bf16_f32 v1, v2, v3
	v_mov_b32_e32 v202, v0
	v_mov_b32_e32 v203, v1
	s_nop 1
	v_permlane32_swap_b32_e32 v200, v202
	v_permlane32_swap_b32_e32 v201, v203
	global_store_dwordx4 v[198:199], v[200:203], off offset:96
	s_barrier

.LBB0_1545:
	v_mov_b32_e32 v204, v150
	v_mov_b32_e32 v205, v149
	v_lshl_add_u64 v[206:207], s[94:95], 0, v[204:205]
	v_lshlrev_b32_e32 v204, 1, v144
	v_lshl_add_u64 v[206:207], v[206:207], 0, v[204:205]
	v_bfe_u32 v208, v192, 5, 1
	v_lshlrev_b32_e32 v208, 3, v208
	v_mov_b32_e32 v209, 0
	v_lshl_add_u64 v[208:209], v[206:207], 0, v[208:209]
	global_load_dwordx4 v[210:213], v[208:209], off
	global_load_dwordx4 v[242:245], v[208:209], off offset:32
	global_load_dwordx4 v[246:249], v[208:209], off offset:64
	global_load_dwordx4 v[250:253], v[208:209], off offset:96
	s_and_b64 vcc, exec, s[70:71]
	s_cbranch_vccnz .LBB0_1084
	v_add_f32_e32 v33, 0, v142
	v_add_f32_e32 v33, v143, v33
	v_add_f32_e32 v33, v160, v33
	v_add_f32_e32 v33, v161, v33
	v_add_f32_e32 v33, v164, v33
	v_add_f32_e32 v33, v165, v33
	v_add_f32_e32 v33, v166, v33
	v_add_f32_e32 v33, v167, v33
	v_add_f32_e32 v33, v168, v33
	v_add_f32_e32 v33, v169, v33
	v_add_f32_e32 v33, v170, v33
	v_add_f32_e32 v33, v171, v33
	v_exp_f32_e32 v40, v34
	v_add_f32_e32 v33, v172, v33
	v_exp_f32_e32 v41, v35
	v_add_f32_e32 v33, v173, v33
	v_exp_f32_e32 v42, v162
	v_add_f32_e32 v33, v174, v33
	v_exp_f32_e32 v43, v163
	v_add_f32_e32 v33, v175, v33
	v_add_f32_e32 v33, v40, v33
	v_add_f32_e32 v33, v41, v33
	v_add_f32_e32 v33, v42, v33
	v_add_f32_e32 v33, v43, v33
	v_mov_b32_e32 v34, v33
	s_nop 1
	v_permlane32_swap_b32_e32 v33, v34
	v_add_f32_e32 v64, v33, v34
	v_fmac_f32_e32 v64, v127, v32
	v_cvt_pk_bf16_f32 v32, v142, v143
	v_cvt_pk_bf16_f32 v33, v160, v161
	v_cvt_pk_bf16_f32 v34, v164, v165
	v_cvt_pk_bf16_f32 v35, v166, v167
	v_cvt_pk_bf16_f32 v36, v168, v169
	v_cvt_pk_bf16_f32 v37, v170, v171
	v_cvt_pk_bf16_f32 v38, v172, v173
	v_cvt_pk_bf16_f32 v39, v174, v175
	v_cvt_pk_bf16_f32 v40, v40, v41
	v_cvt_pk_bf16_f32 v41, v42, v43
	v_cvt_pk_bf16_f32 v42, v149, v149
	v_cvt_pk_bf16_f32 v43, v149, v149
	ds_read_b64_tr_b16 v[44:45], v185 offset:0
	ds_read_b64_tr_b16 v[46:47], v185 offset:0x400
	ds_read_b64_tr_b16 v[48:49], v185 offset:0x800
	ds_read_b64_tr_b16 v[50:51], v185 offset:0xc00
	ds_read_b64_tr_b16 v[52:53], v185 offset:0x1000
	ds_read_b64_tr_b16 v[54:55], v185 offset:0x1400
	ds_read_b64_tr_b16 v[56:57], v185 offset:0x1800
	ds_read_b64_tr_b16 v[58:59], v185 offset:0x1c00
	s_waitcnt lgkmcnt(0)
	s_nop 0
	v_mfma_f32_32x32x16_bf16 v[16:31], v[44:47], v[32:35], v[16:31]
	s_mov_b32 s77, s76
	s_mov_b32 s78, s76
	s_mov_b32 s79, s76
	v_mov_b64_e32 v[44:45], s[76:77]
	v_mov_b64_e32 v[46:47], s[78:79]
	v_mfma_f32_32x32x16_bf16 v[16:31], v[48:51], v[36:39], v[16:31]
	ds_read_b64_tr_b16 v[48:49], v185 offset:0x200
	ds_read_b64_tr_b16 v[50:51], v185 offset:0x600
	v_mfma_f32_32x32x16_bf16 v[16:31], v[52:55], v[40:43], v[16:31]
	ds_read_b64_tr_b16 v[52:53], v185 offset:0xa00
	ds_read_b64_tr_b16 v[54:55], v185 offset:0xe00
	v_mfma_f32_32x32x16_bf16 v[16:31], v[56:59], v[44:47], v[16:31]
	ds_read_b64_tr_b16 v[56:57], v185 offset:0x1200
	ds_read_b64_tr_b16 v[58:59], v185 offset:0x1600
	ds_read_b64_tr_b16 v[60:61], v185 offset:0x1a00
	ds_read_b64_tr_b16 v[62:63], v185 offset:0x1e00
	s_waitcnt lgkmcnt(0)
	v_mfma_f32_32x32x16_bf16 v[0:15], v[48:51], v[32:35], v[0:15]
	v_mov_b32_e32 v127, v64
	v_mfma_f32_32x32x16_bf16 v[0:15], v[52:55], v[36:39], v[0:15]
	v_mfma_f32_32x32x16_bf16 v[0:15], v[56:59], v[40:43], v[0:15]
	v_mfma_f32_32x32x16_bf16 v[0:15], v[60:63], v[44:47], v[0:15]
	s_branch .LBB0_1084
